# safe stack + HC top barrier removed + HGRN2 state pass with double-buffered V^T and no top-of-unit barrier
# baseline (speedup 1.0000x reference)
.LBB0_208:
	s_andn2_b64 vcc, exec, s[6:7]
	s_cbranch_vccnz .LBB0_232
	v_readlane_b32 s6, v252, 8
	s_waitcnt vmcnt(0)
	v_mov_b32_e32 v18, v204
	v_readlane_b32 s7, v252, 9
	s_andn2_b64 vcc, exec, s[6:7]
	v_readfirstlane_b32 s8, v18
	s_cbranch_vccnz .LBB0_232
	s_add_u32 s6, s30, 0xec00000
	s_addc_u32 s7, s31, 0
	s_add_u32 s10, s30, 0x16c00000
	s_addc_u32 s11, s31, 0
	s_ashr_i32 s22, s8, 6
	s_lshl_b32 s34, s22, 3
	s_ashr_i32 s35, s34, 31
	v_readlane_b32 s16, v252, 11
	s_add_u32 s12, s16, s34
	v_readlane_b32 s17, v252, 12
	v_readlane_b32 s0, v252, 13
	s_addc_u32 s13, s17, s35
	s_lshl_b32 s0, s0, 1
	v_and_b32_e32 v19, 63, v18
	s_add_u32 s14, s10, s0
	s_addc_u32 s15, s11, 0
	v_lshlrev_b32_e32 v0, 2, v19
	v_lshl_add_u64 v[2:3], s[14:15], 0, v[0:1]
	s_lshl_b64 s[12:13], s[12:13], 11
	v_lshl_add_u64 v[2:3], v[2:3], 0, s[12:13]
	s_movk_i32 s9, 0x1000
	v_add_co_u32_e32 v4, vcc, s9, v2
	s_movk_i32 s9, 0x2000
	s_nop 0
	v_addc_co_u32_e32 v5, vcc, 0, v3, vcc
	v_add_co_u32_e32 v6, vcc, s9, v2
	s_movk_i32 s9, 0x3000
	s_nop 0
	v_addc_co_u32_e32 v7, vcc, 0, v3, vcc
	global_load_dword v58, v[6:7], off offset:-4096
	global_load_dword v60, v[6:7], off
	global_load_dword v61, v[6:7], off offset:2048
	v_add_co_u32_e32 v6, vcc, s9, v2
	s_movk_i32 s12, 0x90
	s_nop 0
	v_addc_co_u32_e32 v7, vcc, 0, v3, vcc
	global_load_dword v62, v[2:3], off
	global_load_dword v63, v[2:3], off offset:2048
	global_load_dword v64, v[4:5], off offset:2048
	global_load_dword v65, v[6:7], off
	global_load_dword v66, v[6:7], off offset:2048
	v_lshlrev_b32_e32 v2, 1, v18
	v_and_b32_e32 v10, 62, v2
	v_or_b32_e32 v2, s16, v10
	v_mov_b32_e32 v3, s17
	v_ashrrev_i32_e32 v4, 2, v18
	v_lshlrev_b64 v[2:3], 11, v[2:3]
	v_and_b32_e32 v12, -8, v4
	v_lshl_add_u64 v[2:3], s[6:7], 0, v[2:3]
	v_ashrrev_i32_e32 v13, 31, v12
	v_lshl_add_u64 v[2:3], v[2:3], 0, s[0:1]
	v_lshl_add_u64 v[6:7], v[12:13], 1, v[2:3]
	global_load_dwordx4 v[2:5], v[6:7], off
	s_nop 0
	global_load_dwordx4 v[6:9], v[6:7], off offset:2048
	s_lshl_b32 s0, s22, 9
	s_add_i32 s0, s0, 0
	v_mul_lo_u32 v11, v12, s12
	s_cmp_gt_u32 s8, 63
	v_and_b32_e32 v20, 15, v18
	v_add_u32_e32 v21, 0, v11
	v_lshlrev_b32_e32 v11, 2, v18
	v_lshlrev_b32_e32 v16, 3, v19
	s_cselect_b64 s[8:9], -1, 0
	v_mov_b32_e32 v17, v1
	s_lshl_b32 s24, s22, 4
	v_and_b32_e32 v22, 0x7c, v11
	v_add_u32_e32 v11, s0, v16
	v_lshl_add_u64 v[14:15], s[10:11], 0, v[0:1]
	v_add_u32_e32 v59, 0, v16
	v_lshl_add_u64 v[16:17], s[30:31], 0, v[16:17]
	s_mov_b64 s[10:11], 0x1ec00000
	s_ashr_i32 s25, s24, 31
	v_or_b32_e32 v0, s24, v20
	v_lshl_add_u64 v[16:17], v[16:17], 0, s[10:11]
	v_mul_lo_u32 v0, v0, s12
	s_lshl_b64 s[10:11], s[24:25], 1
	v_readlane_b32 s12, v254, 8
	v_readlane_b32 s13, v254, 9
	s_add_u32 s10, s12, s10
	v_add_u32_e32 v24, 0, v0
	s_addc_u32 s11, s13, s11
	v_lshrrev_b32_e32 v0, 1, v18
	s_movk_i32 s0, 0x118
	v_and_b32_e32 v0, 24, v0
	s_cmp_lt_i32 s22, 1
	v_mad_u32_u24 v23, v19, s0, v59
	v_and_b32_e32 v25, 48, v18
	v_lshl_add_u64 v[18:19], s[10:11], 0, v[0:1]
	s_cselect_b64 s[10:11], -1, 0
	s_cmp_lt_i32 s22, 2
	s_cselect_b64 s[12:13], -1, 0
	s_cmp_lt_i32 s22, 3
	s_cselect_b64 s[14:15], -1, 0
	s_cmp_lt_i32 s22, 4
	s_cselect_b64 s[16:17], -1, 0
	s_cmp_lt_i32 s22, 5
	s_cselect_b64 s[18:19], -1, 0
	s_cmp_lt_i32 s22, 6
	v_add_u32_e32 v26, 0, v25
	s_cselect_b64 s[20:21], -1, 0
	s_cmp_lt_i32 s22, 7
	v_mul_u32_u24_e32 v27, 0x90, v20
	v_lshlrev_b32_e32 v0, 8, v20
	s_cselect_b64 s[22:23], -1, 0
	v_lshl_add_u64 v[18:19], v[18:19], 0, v[0:1]
	v_add_u32_e32 v67, v21, v22
	v_add_u32_e32 v68, s24, v23
	v_add_u32_e32 v69, v24, v25
	v_add_u32_e32 v70, v26, v27
	s_mov_b32 s100, 0x5800
	v_readlane_b32 s38, v252, 10
	s_mov_b32 s28, s2
	s_branch .LBB0_212
.LBB0_211:
	v_exp_f32_e32 v54, v51
	v_exp_f32_e32 v55, v49
	v_exp_f32_e32 v51, v48
	v_pk_add_f32 v[34:35], v[52:53], v[34:35] neg_lo:[0,1] neg_hi:[0,1]
	v_pk_add_f32 v[32:33], v[52:53], v[32:33] neg_lo:[0,1] neg_hi:[0,1]
	v_pk_add_f32 v[48:49], v[54:55], 1.0 op_sel_hi:[1,0] neg_lo:[1,0] neg_hi:[1,0]
	v_exp_f32_e32 v54, v47
	v_exp_f32_e32 v55, v45
	v_exp_f32_e32 v47, v44
	v_pk_add_f32 v[30:31], v[52:53], v[30:31] neg_lo:[0,1] neg_hi:[0,1]
	v_pk_add_f32 v[28:29], v[52:53], v[28:29] neg_lo:[0,1] neg_hi:[0,1]
	v_pk_add_f32 v[44:45], v[54:55], 1.0 op_sel_hi:[1,0] neg_lo:[1,0] neg_hi:[1,0]
	v_exp_f32_e32 v54, v43
	v_exp_f32_e32 v55, v41
	v_exp_f32_e32 v43, v40
	v_pk_add_f32 v[26:27], v[52:53], v[26:27] neg_lo:[0,1] neg_hi:[0,1]
	v_pk_add_f32 v[24:25], v[52:53], v[24:25] neg_lo:[0,1] neg_hi:[0,1]
	v_pk_add_f32 v[40:41], v[54:55], 1.0 op_sel_hi:[1,0] neg_lo:[1,0] neg_hi:[1,0]
	v_exp_f32_e32 v54, v39
	v_exp_f32_e32 v55, v37
	v_exp_f32_e32 v39, v36
	v_exp_f32_e32 v50, v50
	v_exp_f32_e32 v46, v46
	v_pk_add_f32 v[36:37], v[54:55], 1.0 op_sel_hi:[1,0] neg_lo:[1,0] neg_hi:[1,0]
	v_exp_f32_e32 v54, v35
	v_exp_f32_e32 v55, v33
	v_exp_f32_e32 v35, v32
	v_exp_f32_e32 v42, v42
	v_exp_f32_e32 v38, v38
	v_pk_mul_f32 v[32:33], v[48:49], v[54:55]
	v_exp_f32_e32 v48, v31
	v_exp_f32_e32 v49, v29
	v_exp_f32_e32 v31, v28
	v_pk_add_f32 v[22:23], v[52:53], v[22:23] neg_lo:[0,1] neg_hi:[0,1]
	v_pk_add_f32 v[20:21], v[52:53], v[20:21] neg_lo:[0,1] neg_hi:[0,1]
	v_pk_mul_f32 v[28:29], v[44:45], v[48:49]
	v_exp_f32_e32 v44, v27
	v_exp_f32_e32 v45, v25
	v_exp_f32_e32 v34, v34
	v_exp_f32_e32 v30, v30
	v_exp_f32_e32 v26, v26
	v_exp_f32_e32 v27, v24
	v_pk_mul_f32 v[24:25], v[40:41], v[44:45]
	v_exp_f32_e32 v22, v22
	v_exp_f32_e32 v40, v23
	v_exp_f32_e32 v23, v20
	v_exp_f32_e32 v41, v21
	v_pk_add_f32 v[50:51], v[50:51], 1.0 op_sel_hi:[1,0] neg_lo:[1,0] neg_hi:[1,0]
	v_pk_add_f32 v[46:47], v[46:47], 1.0 op_sel_hi:[1,0] neg_lo:[1,0] neg_hi:[1,0]
	v_pk_add_f32 v[42:43], v[42:43], 1.0 op_sel_hi:[1,0] neg_lo:[1,0] neg_hi:[1,0]
	v_pk_add_f32 v[38:39], v[38:39], 1.0 op_sel_hi:[1,0] neg_lo:[1,0] neg_hi:[1,0]
	v_pk_mul_f32 v[34:35], v[50:51], v[34:35]
	v_pk_mul_f32 v[30:31], v[46:47], v[30:31]
	v_pk_mul_f32 v[26:27], v[42:43], v[26:27]
	v_pk_mul_f32 v[38:39], v[38:39], v[22:23]
	v_pk_mul_f32 v[36:37], v[36:37], v[40:41]
	v_cvt_pk_bf16_f32 v20, v34, v35
	v_cvt_pk_bf16_f32 v21, v30, v31
	v_cvt_pk_bf16_f32 v22, v26, v27
	v_cvt_pk_bf16_f32 v23, v38, v39
	ds_write_b128 v68, v[20:23]
	v_cvt_pk_bf16_f32 v20, v32, v33
	v_cvt_pk_bf16_f32 v21, v28, v29
	v_cvt_pk_bf16_f32 v22, v24, v25
	v_cvt_pk_bf16_f32 v23, v36, v37
	ds_write_b128 v68, v[20:23] offset:144
	s_waitcnt lgkmcnt(0)
	s_barrier
	ds_read_b128 v[20:23], v69
	ds_read_b128 v[24:27], v70 offset:18432
	ds_read_b128 v[28:31], v70 offset:20736
	ds_read_b128 v[52:55], v70 offset:34560
	ds_read_b128 v[32:35], v70 offset:23040
	ds_read_b128 v[36:39], v70 offset:25344
	ds_read_b128 v[40:43], v70 offset:27648
	ds_read_b128 v[44:47], v70 offset:29952
	ds_read_b128 v[48:51], v70 offset:32256
	s_waitcnt lgkmcnt(7)
	v_mfma_f32_16x16x32_bf16 v[24:27], v[20:23], v[24:27], 0
	s_lshl_b64 s[28:29], s[28:29], 15
	s_movk_i32 s0, 0x2000
	s_waitcnt lgkmcnt(6)
	v_mfma_f32_16x16x32_bf16 v[28:31], v[20:23], v[28:31], 0
	s_waitcnt lgkmcnt(4)
	v_mfma_f32_16x16x32_bf16 v[32:35], v[20:23], v[32:35], 0
	s_waitcnt lgkmcnt(3)
	v_mfma_f32_16x16x32_bf16 v[36:39], v[20:23], v[36:39], 0
	s_waitcnt lgkmcnt(2)
	v_mfma_f32_16x16x32_bf16 v[40:43], v[20:23], v[40:43], 0
	s_waitcnt lgkmcnt(1)
	v_mfma_f32_16x16x32_bf16 v[44:47], v[20:23], v[44:47], 0
	s_waitcnt lgkmcnt(0)
	v_mfma_f32_16x16x32_bf16 v[48:51], v[20:23], v[48:51], 0
	v_mfma_f32_16x16x32_bf16 v[20:23], v[20:23], v[52:55], 0
	ds_read_b128 v[52:55], v69 offset:64
	ds_read_b128 v[72:75], v70 offset:18496
	s_waitcnt lgkmcnt(0)
	v_mfma_f32_16x16x32_bf16 v[24:27], v[52:55], v[72:75], v[24:27]
	ds_read_b128 v[72:75], v70 offset:20800
	s_waitcnt lgkmcnt(0)
	v_mfma_f32_16x16x32_bf16 v[28:31], v[52:55], v[72:75], v[28:31]
	ds_read_b128 v[72:75], v70 offset:23104
	s_nop 3
	v_cvt_pk_bf16_f32 v24, v24, v25
	v_cvt_pk_bf16_f32 v25, v26, v27
	s_waitcnt lgkmcnt(0)
	v_mfma_f32_16x16x32_bf16 v[32:35], v[52:55], v[72:75], v[32:35]
	ds_read_b128 v[72:75], v70 offset:25408
	v_lshl_add_u64 v[26:27], v[18:19], 0, s[28:29]
	global_store_dwordx2 v[26:27], v[24:25], off
	s_waitcnt lgkmcnt(0)
	v_mfma_f32_16x16x32_bf16 v[36:39], v[52:55], v[72:75], v[36:39]
	ds_read_b128 v[72:75], v70 offset:27712
	v_cvt_pk_bf16_f32 v24, v28, v29
	v_add_co_u32_e32 v28, vcc, s0, v26
	s_waitcnt lgkmcnt(0)
	v_mfma_f32_16x16x32_bf16 v[40:43], v[52:55], v[72:75], v[40:43]
	ds_read_b128 v[72:75], v70 offset:30016
	v_cvt_pk_bf16_f32 v25, v30, v31
	v_addc_co_u32_e32 v29, vcc, 0, v27, vcc
	s_waitcnt lgkmcnt(0)
	v_mfma_f32_16x16x32_bf16 v[44:47], v[52:55], v[72:75], v[44:47]
	ds_read_b128 v[72:75], v70 offset:32320
	global_store_dwordx2 v[28:29], v[24:25], off offset:-4096
	v_cvt_pk_bf16_f32 v24, v32, v33
	s_waitcnt lgkmcnt(0)
	v_mfma_f32_16x16x32_bf16 v[48:51], v[52:55], v[72:75], v[48:51]
	ds_read_b128 v[72:75], v70 offset:34624
	v_cvt_pk_bf16_f32 v25, v34, v35
	s_movk_i32 s0, 0x4000
	global_store_dwordx2 v[28:29], v[24:25], off
	v_add_co_u32_e32 v28, vcc, s0, v26
	s_waitcnt lgkmcnt(0)
	v_mfma_f32_16x16x32_bf16 v[20:23], v[52:55], v[72:75], v[20:23]
	v_cvt_pk_bf16_f32 v24, v36, v37
	v_cvt_pk_bf16_f32 v25, v38, v39
	v_addc_co_u32_e32 v29, vcc, 0, v27, vcc
	global_store_dwordx2 v[28:29], v[24:25], off offset:-4096
	v_cvt_pk_bf16_f32 v24, v40, v41
	v_cvt_pk_bf16_f32 v25, v42, v43
	s_movk_i32 s0, 0x6000
	global_store_dwordx2 v[28:29], v[24:25], off
	v_add_co_u32_e32 v28, vcc, s0, v26
	v_cvt_pk_bf16_f32 v20, v20, v21
	s_nop 0
	v_addc_co_u32_e32 v29, vcc, 0, v27, vcc
	v_cvt_pk_bf16_f32 v21, v22, v23
	v_add_co_u32_e32 v22, vcc, 0x7000, v26
	v_cvt_pk_bf16_f32 v24, v44, v45
	v_cvt_pk_bf16_f32 v25, v46, v47
	v_addc_co_u32_e32 v23, vcc, 0, v27, vcc
	v_readlane_b32 s0, v252, 56
	global_store_dwordx2 v[28:29], v[24:25], off offset:-4096
	v_cvt_pk_bf16_f32 v24, v48, v49
	v_cvt_pk_bf16_f32 v25, v50, v51
	s_add_i32 s38, s38, s0
	s_and_b64 vcc, exec, s[24:25]
	s_mov_b32 s28, s39
	global_store_dwordx2 v[28:29], v[24:25], off
	global_store_dwordx2 v[22:23], v[20:21], off
	s_cbranch_vccnz .LBB0_232
	v_add_u32_e32 v67, s100, v67
	v_add_u32_e32 v70, s100, v70
	s_sub_i32 s100, 0, s100
.LBB0_212:
	s_waitcnt vmcnt(1)
	v_and_b32_e32 v0, 0xffff, v2
	v_lshrrev_b32_e32 v20, 16, v2
	s_mov_b32 s0, 0xffff0000
	v_lshlrev_b32_e32 v50, 16, v62
	v_and_b32_e32 v51, 0xffff0000, v62
	s_waitcnt vmcnt(0)
	v_lshl_or_b32 v0, v6, 16, v0
	v_and_or_b32 v20, v6, s0, v20
	v_add_u32_e32 v21, 0x4800, v67
	v_and_b32_e32 v49, 0xffff0000, v63
	v_lshlrev_b32_e32 v48, 16, v63
	v_pk_add_f32 v[34:35], v[50:51], 0 op_sel_hi:[1,0]
	ds_write2_b32 v21, v0, v20 offset1:36
	v_and_b32_e32 v0, 0xffff, v3
	v_lshrrev_b32_e32 v20, 16, v3
	v_and_b32_e32 v47, 0xffff0000, v58
	v_lshlrev_b32_e32 v46, 16, v58
	v_pk_add_f32 v[32:33], v[34:35], v[48:49]
	v_lshl_or_b32 v0, v7, 16, v0
	v_and_or_b32 v20, v7, s0, v20
	v_and_b32_e32 v45, 0xffff0000, v64
	v_lshlrev_b32_e32 v44, 16, v64
	v_pk_add_f32 v[30:31], v[32:33], v[46:47]
	ds_write2_b32 v21, v0, v20 offset0:72 offset1:108
	v_and_b32_e32 v0, 0xffff, v4
	v_lshrrev_b32_e32 v20, 16, v4
	v_and_b32_e32 v43, 0xffff0000, v60
	v_lshlrev_b32_e32 v42, 16, v60
	v_pk_add_f32 v[28:29], v[30:31], v[44:45]
	v_lshl_or_b32 v0, v8, 16, v0
	v_and_or_b32 v20, v8, s0, v20
	v_and_b32_e32 v41, 0xffff0000, v61
	v_lshlrev_b32_e32 v40, 16, v61
	v_pk_add_f32 v[26:27], v[28:29], v[42:43]
	s_add_i32 s39, s28, s46
	ds_write2_b32 v21, v0, v20 offset0:144 offset1:180
	v_and_b32_e32 v0, 0xffff, v5
	v_lshrrev_b32_e32 v20, 16, v5
	v_and_b32_e32 v39, 0xffff0000, v65
	v_lshlrev_b32_e32 v38, 16, v65
	v_pk_add_f32 v[24:25], v[26:27], v[40:41]
	s_cmpk_gt_i32 s39, 0xfff
	v_lshl_or_b32 v0, v9, 16, v0
	v_and_or_b32 v20, v9, s0, v20
	v_and_b32_e32 v37, 0xffff0000, v66
	v_lshlrev_b32_e32 v36, 16, v66
	v_pk_add_f32 v[22:23], v[24:25], v[38:39]
	s_cselect_b64 s[24:25], -1, 0
	ds_write2_b32 v21, v0, v20 offset0:216 offset1:252
	v_pk_add_f32 v[20:21], v[22:23], v[36:37]
	s_and_b64 vcc, exec, s[24:25]
	ds_write_b64 v11, v[20:21] offset:36864
	s_cbranch_vccnz .LBB0_214
	v_readlane_b32 s0, v252, 56
	s_add_i32 s0, s0, s38
	s_and_b32 s0, s0, 0xf00
	s_ashr_i32 s29, s39, 4
	s_add_i32 s0, s0, s29
	s_ashr_i32 s29, s0, 31
	s_lshr_b32 s29, s29, 24
	s_add_i32 s29, s0, s29
	s_and_b32 s36, s29, 0xffffff00
	s_sub_i32 s36, s0, s36
	s_ashr_i32 s40, s29, 11
	s_ashr_i32 s41, s40, 31
	s_ashr_i32 s37, s36, 31
	s_lshl_b64 s[40:41], s[40:41], 14
	s_lshl_b64 s[36:37], s[36:37], 6
	s_add_u32 s40, s40, s36
	s_addc_u32 s41, s41, s37
	s_add_u32 s36, s40, s34
	s_addc_u32 s37, s41, s35
	s_and_b32 s0, s29, 0x700
	v_lshl_add_u64 v[2:3], v[14:15], 0, s[0:1]
	s_lshl_b64 s[36:37], s[36:37], 11
	v_lshl_add_u64 v[2:3], v[2:3], 0, s[36:37]
	s_movk_i32 s29, 0x1000
	v_add_co_u32_e32 v4, vcc, s29, v2
	s_movk_i32 s29, 0x2000
	s_nop 0
	v_addc_co_u32_e32 v5, vcc, 0, v3, vcc
	v_add_co_u32_e32 v6, vcc, s29, v2
	s_movk_i32 s29, 0x3000
	s_nop 0
	v_addc_co_u32_e32 v7, vcc, 0, v3, vcc
	global_load_dword v58, v[6:7], off offset:-4096
	global_load_dword v60, v[6:7], off
	global_load_dword v61, v[6:7], off offset:2048
	v_add_co_u32_e32 v6, vcc, s29, v2
	s_nop 1
	v_addc_co_u32_e32 v7, vcc, 0, v3, vcc
	global_load_dword v62, v[2:3], off
	global_load_dword v63, v[2:3], off offset:2048
	global_load_dword v64, v[4:5], off offset:2048
	global_load_dword v65, v[6:7], off
	global_load_dword v66, v[6:7], off offset:2048
	v_mov_b32_e32 v3, s41
	v_or_b32_e32 v2, s40, v10
	v_lshlrev_b64 v[2:3], 11, v[2:3]
	v_lshl_add_u64 v[2:3], s[6:7], 0, v[2:3]
	v_lshl_add_u64 v[2:3], v[2:3], 0, s[0:1]
	v_lshl_add_u64 v[6:7], v[12:13], 1, v[2:3]
	global_load_dwordx4 v[2:5], v[6:7], off
	s_nop 0
	global_load_dwordx4 v[6:9], v[6:7], off offset:2048
